# context-attention tasks: 7 K tiles / 3 V k-steps of loads in flight (ring of 14 quads, counted vmcnt) instead of one step ahead
# speedup vs baseline: 1.0045x; 1.0045x over previous
.LBB0_524:
	s_and_b32 s0, s2, 0xffffff00
	s_and_b32 s1, s11, 0xf0
	v_or_b32_e32 v0, s1, v118
	s_and_b32 s18, s4, 0x3c0
	s_ashr_i32 s1, s0, 31
	s_lshl_b32 s6, s18, 1
	s_lshl_b64 s[16:17], s[0:1], 12
	s_add_u32 s16, s44, s16
	v_or_b32_e32 v34, s0, v0
	s_addc_u32 s17, s45, s17
	v_ashrrev_i32_e32 v35, 31, v34
	s_add_u32 s16, s16, s6
	v_lshlrev_b64 v[0:1], 12, v[34:35]
	s_addc_u32 s17, s17, 0
	v_lshl_add_u64 v[0:1], s[44:45], 0, v[0:1]
	v_lshl_add_u64 v[40:41], s[16:17], 0, v[148:149]
	s_movk_i32 s16, 0x4000
	v_lshl_add_u64 v[0:1], v[0:1], 0, s[6:7]
	v_add_co_u32_e32 v12, vcc, s16, v40
	v_lshl_add_u64 v[4:5], v[36:37], 1, v[0:1]
	s_nop 0
	v_addc_co_u32_e32 v13, vcc, 0, v41, vcc
	global_load_dwordx4 v[0:3], v[4:5], off
	s_nop 0
	global_load_dwordx4 v[4:7], v[4:5], off offset:64
	global_load_dwordx4 v[190:193], v[40:41], off offset:2048
	global_load_dwordx4 v[194:197], v[40:41], off offset:2112
	v_add_co_u32_e32 v130, vcc, 0x4000, v40
	v_addc_co_u32_e32 v131, vcc, 0, v41, vcc
	global_load_dwordx4 v[198:201], v[130:131], off offset:2048
	global_load_dwordx4 v[202:205], v[130:131], off offset:2112
	v_add_co_u32_e32 v130, vcc, 0x20000, v40
	v_addc_co_u32_e32 v131, vcc, 0, v41, vcc
	global_load_dwordx4 v[206:209], v[130:131], off offset:2048
	global_load_dwordx4 v[210:213], v[130:131], off offset:2112
	v_add_co_u32_e32 v130, vcc, 0x24000, v40
	v_addc_co_u32_e32 v131, vcc, 0, v41, vcc
	global_load_dwordx4 v[214:217], v[130:131], off offset:2048
	global_load_dwordx4 v[218:221], v[130:131], off offset:2112
	v_add_co_u32_e32 v130, vcc, 0x40000, v40
	v_addc_co_u32_e32 v131, vcc, 0, v41, vcc
	global_load_dwordx4 v[222:225], v[130:131], off offset:2048
	global_load_dwordx4 v[226:229], v[130:131], off offset:2112
	v_add_co_u32_e32 v130, vcc, 0x44000, v40
	v_addc_co_u32_e32 v131, vcc, 0, v41, vcc
	global_load_dwordx4 v[230:233], v[130:131], off offset:2048
	global_load_dwordx4 v[234:237], v[130:131], off offset:2112
	v_add_co_u32_e32 v130, vcc, 0x60000, v40
	v_addc_co_u32_e32 v131, vcc, 0, v41, vcc
	global_load_dwordx4 v[238:241], v[130:131], off offset:2048
	global_load_dwordx4 v[242:245], v[130:131], off offset:2112
	s_nop 0
	s_nop 0
	s_nop 0
	s_mul_i32 s18, s18, 0x12000
	s_add_u32 s16, s46, s18
	s_addc_u32 s17, s47, 0
	s_waitcnt vmcnt(13)
	v_mfma_f32_16x16x32_bf16 v[20:23], v[190:193], v[0:3], 0
	s_waitcnt vmcnt(12)
	v_mfma_f32_16x16x32_bf16 v[16:19], v[194:197], v[4:7], v[20:23]
	v_add_co_u32_e32 v130, vcc, 0x64000, v40
	v_addc_co_u32_e32 v131, vcc, 0, v41, vcc
	global_load_dwordx4 v[190:193], v[130:131], off offset:2048
	global_load_dwordx4 v[194:197], v[130:131], off offset:2112
	s_nop 7
	v_pk_mul_f32 v[74:75], v[18:19], s[12:13] op_sel_hi:[1,0]
	v_pk_mul_f32 v[76:77], v[16:17], s[12:13] op_sel_hi:[1,0]
	v_max_f32_e32 v16, v74, v75
	v_max3_f32 v24, v76, v77, v16
	s_nop 1
	s_nop 0
	s_waitcnt vmcnt(13)
	v_mfma_f32_16x16x32_bf16 v[8:11], v[198:201], v[0:3], 0
	s_waitcnt vmcnt(12)
	v_mfma_f32_16x16x32_bf16 v[8:11], v[202:205], v[4:7], v[8:11]
	v_add_co_u32_e32 v130, vcc, 0x80000, v40
	v_addc_co_u32_e32 v131, vcc, 0, v41, vcc
	global_load_dwordx4 v[198:201], v[130:131], off offset:2048
	global_load_dwordx4 v[202:205], v[130:131], off offset:2112
	s_nop 7
	v_pk_mul_f32 v[70:71], v[10:11], s[12:13] op_sel_hi:[1,0]
	v_pk_mul_f32 v[72:73], v[8:9], s[12:13] op_sel_hi:[1,0]
	v_max_f32_e32 v8, v70, v71
	v_max3_f32 v8, v72, v73, v8
	v_max3_f32 v24, v24, s69, v8
	s_nop 1
	s_nop 0
	s_waitcnt vmcnt(13)
	v_mfma_f32_16x16x32_bf16 v[16:19], v[206:209], v[0:3], 0
	s_waitcnt vmcnt(12)
	v_mfma_f32_16x16x32_bf16 v[16:19], v[210:213], v[4:7], v[16:19]
	v_add_co_u32_e32 v130, vcc, 0x84000, v40
	v_addc_co_u32_e32 v131, vcc, 0, v41, vcc
	global_load_dwordx4 v[206:209], v[130:131], off offset:2048
	global_load_dwordx4 v[210:213], v[130:131], off offset:2112
	s_nop 7
	v_pk_mul_f32 v[66:67], v[18:19], s[12:13] op_sel_hi:[1,0]
	v_pk_mul_f32 v[68:69], v[16:17], s[12:13] op_sel_hi:[1,0]
	v_max_f32_e32 v16, v66, v67
	v_max3_f32 v25, v68, v69, v16
	s_nop 1
	s_nop 0
	s_waitcnt vmcnt(13)
	v_mfma_f32_16x16x32_bf16 v[8:11], v[214:217], v[0:3], 0
	s_waitcnt vmcnt(12)
	v_mfma_f32_16x16x32_bf16 v[8:11], v[218:221], v[4:7], v[8:11]
	v_add_co_u32_e32 v130, vcc, 0xa0000, v40
	v_addc_co_u32_e32 v131, vcc, 0, v41, vcc
	global_load_dwordx4 v[214:217], v[130:131], off offset:2048
	global_load_dwordx4 v[218:221], v[130:131], off offset:2112
	s_nop 7
	v_pk_mul_f32 v[62:63], v[10:11], s[12:13] op_sel_hi:[1,0]
	v_pk_mul_f32 v[64:65], v[8:9], s[12:13] op_sel_hi:[1,0]
	v_max_f32_e32 v8, v62, v63
	v_max3_f32 v8, v64, v65, v8
	v_max3_f32 v24, v24, v25, v8
	s_nop 1
	s_nop 0
	s_waitcnt vmcnt(13)
	v_mfma_f32_16x16x32_bf16 v[16:19], v[222:225], v[0:3], 0
	s_waitcnt vmcnt(12)
	v_mfma_f32_16x16x32_bf16 v[16:19], v[226:229], v[4:7], v[16:19]
	v_add_co_u32_e32 v130, vcc, 0xa4000, v40
	v_addc_co_u32_e32 v131, vcc, 0, v41, vcc
	global_load_dwordx4 v[222:225], v[130:131], off offset:2048
	global_load_dwordx4 v[226:229], v[130:131], off offset:2112
	s_nop 7
	v_pk_mul_f32 v[58:59], v[18:19], s[12:13] op_sel_hi:[1,0]
	v_pk_mul_f32 v[60:61], v[16:17], s[12:13] op_sel_hi:[1,0]
	v_max_f32_e32 v16, v58, v59
	v_max3_f32 v25, v60, v61, v16
	s_nop 1
	s_nop 0
	s_waitcnt vmcnt(13)
	v_mfma_f32_16x16x32_bf16 v[8:11], v[230:233], v[0:3], 0
	s_waitcnt vmcnt(12)
	v_mfma_f32_16x16x32_bf16 v[8:11], v[234:237], v[4:7], v[8:11]
	v_add_co_u32_e32 v130, vcc, 0xc0000, v40
	v_addc_co_u32_e32 v131, vcc, 0, v41, vcc
	global_load_dwordx4 v[230:233], v[130:131], off offset:2048
	global_load_dwordx4 v[234:237], v[130:131], off offset:2112
	s_nop 7
	v_pk_mul_f32 v[54:55], v[10:11], s[12:13] op_sel_hi:[1,0]
	v_pk_mul_f32 v[56:57], v[8:9], s[12:13] op_sel_hi:[1,0]
	v_max_f32_e32 v8, v54, v55
	v_max3_f32 v8, v56, v57, v8
	v_max3_f32 v24, v24, v25, v8
	s_nop 1
	s_nop 0
	s_waitcnt vmcnt(13)
	v_mfma_f32_16x16x32_bf16 v[16:19], v[238:241], v[0:3], 0
	s_waitcnt vmcnt(12)
	v_mfma_f32_16x16x32_bf16 v[16:19], v[242:245], v[4:7], v[16:19]
	v_add_co_u32_e32 v130, vcc, 0xc4000, v40
	v_addc_co_u32_e32 v131, vcc, 0, v41, vcc
	global_load_dwordx4 v[238:241], v[130:131], off offset:2048
	global_load_dwordx4 v[242:245], v[130:131], off offset:2112
	s_nop 7
	v_pk_mul_f32 v[50:51], v[18:19], s[12:13] op_sel_hi:[1,0]
	v_pk_mul_f32 v[52:53], v[16:17], s[12:13] op_sel_hi:[1,0]
	v_max_f32_e32 v16, v50, v51
	v_max3_f32 v25, v52, v53, v16
	s_nop 1
	s_nop 0
	s_waitcnt vmcnt(13)
	v_mfma_f32_16x16x32_bf16 v[8:11], v[190:193], v[0:3], 0
	s_waitcnt vmcnt(12)
	v_mfma_f32_16x16x32_bf16 v[8:11], v[194:197], v[4:7], v[8:11]
	v_add_co_u32_e32 v130, vcc, 0xe0000, v40
	v_addc_co_u32_e32 v131, vcc, 0, v41, vcc
	global_load_dwordx4 v[190:193], v[130:131], off offset:2048
	global_load_dwordx4 v[194:197], v[130:131], off offset:2112
	s_nop 7
	v_pk_mul_f32 v[46:47], v[10:11], s[12:13] op_sel_hi:[1,0]
	v_pk_mul_f32 v[48:49], v[8:9], s[12:13] op_sel_hi:[1,0]
	v_max_f32_e32 v8, v46, v47
	v_max3_f32 v8, v48, v49, v8
	v_max3_f32 v24, v24, v25, v8
	s_nop 1
	s_nop 0
	s_waitcnt vmcnt(13)
	v_mfma_f32_16x16x32_bf16 v[16:19], v[198:201], v[0:3], 0
	s_waitcnt vmcnt(12)
	v_mfma_f32_16x16x32_bf16 v[16:19], v[202:205], v[4:7], v[16:19]
	v_add_co_u32_e32 v130, vcc, 0xe4000, v40
	v_addc_co_u32_e32 v131, vcc, 0, v41, vcc
	global_load_dwordx4 v[198:201], v[130:131], off offset:2048
	global_load_dwordx4 v[202:205], v[130:131], off offset:2112
	s_nop 7
	v_pk_mul_f32 v[42:43], v[18:19], s[12:13] op_sel_hi:[1,0]
	v_pk_mul_f32 v[44:45], v[16:17], s[12:13] op_sel_hi:[1,0]
	v_max_f32_e32 v16, v42, v43
	v_max3_f32 v25, v44, v45, v16
	s_nop 1
	s_nop 0
	s_waitcnt vmcnt(13)
	v_mfma_f32_16x16x32_bf16 v[8:11], v[206:209], v[0:3], 0
	s_waitcnt vmcnt(12)
	v_mfma_f32_16x16x32_bf16 v[8:11], v[210:213], v[4:7], v[8:11]
	s_nop 7
	v_pk_mul_f32 v[28:29], v[10:11], s[12:13] op_sel_hi:[1,0]
	v_pk_mul_f32 v[30:31], v[8:9], s[12:13] op_sel_hi:[1,0]
	v_max_f32_e32 v8, v28, v29
	v_max3_f32 v8, v30, v31, v8
	v_max3_f32 v84, v24, v25, v8
	s_nop 1
	s_nop 0
	s_waitcnt vmcnt(11)
	v_mfma_f32_16x16x32_bf16 v[16:19], v[214:217], v[0:3], 0
	s_waitcnt vmcnt(10)
	v_mfma_f32_16x16x32_bf16 v[16:19], v[218:221], v[4:7], v[16:19]
	s_nop 7
	v_pk_mul_f32 v[24:25], v[18:19], s[12:13] op_sel_hi:[1,0]
	v_pk_mul_f32 v[26:27], v[16:17], s[12:13] op_sel_hi:[1,0]
	v_max_f32_e32 v16, v24, v25
	v_max3_f32 v85, v26, v27, v16
	s_nop 1
	s_waitcnt vmcnt(9)
	v_mfma_f32_16x16x32_bf16 v[8:11], v[222:225], v[0:3], 0
	s_waitcnt vmcnt(8)
	v_mfma_f32_16x16x32_bf16 v[10:13], v[226:229], v[4:7], v[8:11]
	s_nop 7
	v_pk_mul_f32 v[8:9], v[12:13], s[12:13] op_sel_hi:[1,0]
	v_pk_mul_f32 v[22:23], v[10:11], s[12:13] op_sel_hi:[1,0]
	v_max_f32_e32 v10, v8, v9
	v_max3_f32 v10, v22, v23, v10
	v_max3_f32 v92, v84, v85, v10
	v_add_co_u32_e32 v10, vcc, s18, v40
	s_nop 1
	v_addc_co_u32_e32 v11, vcc, 0, v41, vcc
	s_waitcnt vmcnt(7)
	v_mfma_f32_16x16x32_bf16 v[16:19], v[230:233], v[0:3], 0
	s_waitcnt vmcnt(6)
	v_mfma_f32_16x16x32_bf16 v[16:19], v[234:237], v[4:7], v[16:19]
	s_nop 7
	v_pk_mul_f32 v[10:11], v[18:19], s[12:13] op_sel_hi:[1,0]
	v_pk_mul_f32 v[16:17], v[16:17], s[12:13] op_sel_hi:[1,0]
	v_max_f32_e32 v18, v10, v11
	v_max3_f32 v93, v16, v17, v18
	v_add_co_u32_e32 v18, vcc, s18, v40
	s_nop 1
	v_addc_co_u32_e32 v19, vcc, 0, v41, vcc
	s_waitcnt vmcnt(5)
	v_mfma_f32_16x16x32_bf16 v[12:15], v[238:241], v[0:3], 0
	s_waitcnt vmcnt(4)
	v_mfma_f32_16x16x32_bf16 v[18:21], v[242:245], v[4:7], v[12:15]
	s_nop 7
	v_pk_mul_f32 v[12:13], v[20:21], s[12:13] op_sel_hi:[1,0]
	v_pk_mul_f32 v[18:19], v[18:19], s[12:13] op_sel_hi:[1,0]
	v_max_f32_e32 v14, v12, v13
	v_max3_f32 v14, v18, v19, v14
	v_max3_f32 v96, v92, v93, v14
	v_add_co_u32_e32 v14, vcc, s18, v40
	s_nop 1
	v_addc_co_u32_e32 v15, vcc, 0, v41, vcc
	s_waitcnt vmcnt(3)
	v_mfma_f32_16x16x32_bf16 v[80:83], v[190:193], v[0:3], 0
	s_waitcnt vmcnt(2)
	v_mfma_f32_16x16x32_bf16 v[80:83], v[194:197], v[4:7], v[80:83]
	s_nop 7
	v_pk_mul_f32 v[14:15], v[82:83], s[12:13] op_sel_hi:[1,0]
	v_pk_mul_f32 v[20:21], v[80:81], s[12:13] op_sel_hi:[1,0]
	v_max_f32_e32 v40, v14, v15
	v_max3_f32 v40, v20, v21, v40
	s_waitcnt vmcnt(1)
	v_mfma_f32_16x16x32_bf16 v[0:3], v[198:201], v[0:3], 0
	s_waitcnt vmcnt(0)
	v_mfma_f32_16x16x32_bf16 v[2:5], v[202:205], v[4:7], v[0:3]
	s_nop 7
	v_pk_mul_f32 v[0:1], v[4:5], s[12:13] op_sel_hi:[1,0]
	v_pk_mul_f32 v[2:3], v[2:3], s[12:13] op_sel_hi:[1,0]
	v_max_f32_e32 v4, v0, v1
	v_max3_f32 v4, v2, v3, v4
	v_max3_f32 v4, v96, v40, v4
	ds_bpermute_b32 v5, v78, v4
	s_lshl_b64 s[0:1], s[0:1], 1
	s_add_u32 s0, s16, s0
	s_addc_u32 s1, s17, s1
	v_lshl_add_u64 v[40:41], s[0:1], 0, v[32:33]
	v_mov_b32_e32 v246, v40
	v_mov_b32_e32 v247, v41
	v_add_co_u32_e32 v248, vcc, 0x120000, v40
	v_addc_co_u32_e32 v249, vcc, 0, v41, vcc
	v_add_co_u32_e32 v250, vcc, 0x240000, v40
	v_addc_co_u32_e32 v251, vcc, 0, v41, vcc
	v_add_co_u32_e32 v252, vcc, 0x360000, v40
	v_addc_co_u32_e32 v253, vcc, 0, v41, vcc
	global_load_dwordx4 v[190:193], v[246:247], off
	global_load_dwordx4 v[194:197], v[248:249], off
	global_load_dwordx4 v[198:201], v[250:251], off
	global_load_dwordx4 v[202:205], v[252:253], off
	global_load_dwordx4 v[206:209], v[246:247], off offset:64
	global_load_dwordx4 v[210:213], v[248:249], off offset:64
	global_load_dwordx4 v[214:217], v[250:251], off offset:64
	global_load_dwordx4 v[218:221], v[252:253], off offset:64
	global_load_dwordx4 v[222:225], v[246:247], off offset:128
	global_load_dwordx4 v[226:229], v[248:249], off offset:128
	global_load_dwordx4 v[230:233], v[250:251], off offset:128
	global_load_dwordx4 v[234:237], v[252:253], off offset:128
	s_waitcnt lgkmcnt(0)
	v_max_f32_e32 v5, v5, v5
	v_max_f32_e32 v4, v4, v5
	ds_bpermute_b32 v5, v79, v4
	s_mov_b32 s0, 0x240000
	s_waitcnt lgkmcnt(0)
	v_max_f32_e32 v5, v5, v5
	v_max_f32_e32 v4, v4, v5
	v_sub_f32_e32 v6, v77, v4
	v_mul_f32_e32 v6, 0x3fb8aa3b, v6
	v_exp_f32_e32 v77, v6
	v_sub_f32_e32 v6, v74, v4
	v_mul_f32_e32 v6, 0x3fb8aa3b, v6
	v_exp_f32_e32 v74, v6
	v_sub_f32_e32 v6, v75, v4
	v_mul_f32_e32 v6, 0x3fb8aa3b, v6
	v_exp_f32_e32 v75, v6
	v_sub_f32_e32 v6, v72, v4
	v_mul_f32_e32 v6, 0x3fb8aa3b, v6
	v_exp_f32_e32 v72, v6
	v_sub_f32_e32 v6, v73, v4
	v_mul_f32_e32 v6, 0x3fb8aa3b, v6
	v_exp_f32_e32 v73, v6
	v_sub_f32_e32 v6, v70, v4
	v_mul_f32_e32 v6, 0x3fb8aa3b, v6
	v_exp_f32_e32 v70, v6
	v_sub_f32_e32 v6, v71, v4
	v_mul_f32_e32 v6, 0x3fb8aa3b, v6
	v_exp_f32_e32 v71, v6
	v_sub_f32_e32 v6, v68, v4
	v_mul_f32_e32 v6, 0x3fb8aa3b, v6
	v_exp_f32_e32 v68, v6
	v_sub_f32_e32 v6, v69, v4
	v_mul_f32_e32 v6, 0x3fb8aa3b, v6
	v_exp_f32_e32 v69, v6
	v_sub_f32_e32 v6, v66, v4
	v_mul_f32_e32 v6, 0x3fb8aa3b, v6
	v_exp_f32_e32 v66, v6
	v_sub_f32_e32 v6, v67, v4
	v_mul_f32_e32 v6, 0x3fb8aa3b, v6
	v_exp_f32_e32 v67, v6
	v_sub_f32_e32 v6, v64, v4
	v_mul_f32_e32 v6, 0x3fb8aa3b, v6
	v_exp_f32_e32 v64, v6
	v_sub_f32_e32 v6, v65, v4
	v_mul_f32_e32 v6, 0x3fb8aa3b, v6
	v_exp_f32_e32 v65, v6
	v_sub_f32_e32 v6, v62, v4
	v_mul_f32_e32 v6, 0x3fb8aa3b, v6
	v_exp_f32_e32 v62, v6
	v_sub_f32_e32 v6, v63, v4
	v_mul_f32_e32 v6, 0x3fb8aa3b, v6
	v_exp_f32_e32 v63, v6
	v_sub_f32_e32 v6, v60, v4
	v_mul_f32_e32 v6, 0x3fb8aa3b, v6
	v_exp_f32_e32 v60, v6
	v_sub_f32_e32 v6, v61, v4
	v_mul_f32_e32 v6, 0x3fb8aa3b, v6
	v_exp_f32_e32 v61, v6
	v_sub_f32_e32 v6, v58, v4
	v_mul_f32_e32 v6, 0x3fb8aa3b, v6
	v_exp_f32_e32 v58, v6
	v_sub_f32_e32 v6, v59, v4
	v_mul_f32_e32 v6, 0x3fb8aa3b, v6
	v_exp_f32_e32 v59, v6
	v_sub_f32_e32 v6, v56, v4
	v_mul_f32_e32 v6, 0x3fb8aa3b, v6
	v_exp_f32_e32 v56, v6
	v_sub_f32_e32 v6, v57, v4
	v_mul_f32_e32 v6, 0x3fb8aa3b, v6
	v_exp_f32_e32 v57, v6
	v_sub_f32_e32 v6, v54, v4
	v_mul_f32_e32 v6, 0x3fb8aa3b, v6
	v_exp_f32_e32 v54, v6
	v_sub_f32_e32 v6, v55, v4
	v_mul_f32_e32 v6, 0x3fb8aa3b, v6
	v_exp_f32_e32 v55, v6
	v_sub_f32_e32 v6, v52, v4
	v_mul_f32_e32 v6, 0x3fb8aa3b, v6
	v_exp_f32_e32 v52, v6
	v_sub_f32_e32 v6, v53, v4
	v_mul_f32_e32 v6, 0x3fb8aa3b, v6
	v_exp_f32_e32 v53, v6
	v_sub_f32_e32 v6, v50, v4
	v_mul_f32_e32 v6, 0x3fb8aa3b, v6
	v_exp_f32_e32 v50, v6
	v_sub_f32_e32 v6, v51, v4
	v_mul_f32_e32 v6, 0x3fb8aa3b, v6
	v_exp_f32_e32 v51, v6
	v_sub_f32_e32 v6, v48, v4
	v_mul_f32_e32 v6, 0x3fb8aa3b, v6
	v_exp_f32_e32 v48, v6
	v_sub_f32_e32 v6, v49, v4
	v_sub_f32_e32 v5, v76, v4
	v_mul_f32_e32 v6, 0x3fb8aa3b, v6
	v_mul_f32_e32 v5, 0x3fb8aa3b, v5
	v_exp_f32_e32 v49, v6
	v_sub_f32_e32 v6, v46, v4
	v_exp_f32_e32 v76, v5
	v_mul_f32_e32 v6, 0x3fb8aa3b, v6
	v_exp_f32_e32 v80, v6
	v_sub_f32_e32 v6, v47, v4
	v_mul_f32_e32 v6, 0x3fb8aa3b, v6
	v_exp_f32_e32 v81, v6
	v_sub_f32_e32 v6, v44, v4
	v_add_f32_e32 v5, 0, v76
	v_mul_f32_e32 v6, 0x3fb8aa3b, v6
	v_add_f32_e32 v5, v77, v5
	v_exp_f32_e32 v82, v6
	v_sub_f32_e32 v6, v45, v4
	v_add_f32_e32 v5, v74, v5
	v_mul_f32_e32 v6, 0x3fb8aa3b, v6
	v_add_f32_e32 v5, v75, v5
	v_exp_f32_e32 v83, v6
	v_sub_f32_e32 v6, v42, v4
	v_add_f32_e32 v5, v72, v5
	v_mul_f32_e32 v6, 0x3fb8aa3b, v6
	v_add_f32_e32 v5, v73, v5
	v_exp_f32_e32 v84, v6
	v_sub_f32_e32 v6, v43, v4
	v_add_f32_e32 v5, v70, v5
	v_mul_f32_e32 v6, 0x3fb8aa3b, v6
	v_add_f32_e32 v5, v71, v5
	v_exp_f32_e32 v85, v6
	v_sub_f32_e32 v6, v30, v4
	v_add_f32_e32 v5, v68, v5
	v_mul_f32_e32 v6, 0x3fb8aa3b, v6
	v_add_f32_e32 v5, v69, v5
	v_exp_f32_e32 v86, v6
	v_sub_f32_e32 v6, v31, v4
	v_add_f32_e32 v5, v66, v5
	v_mul_f32_e32 v6, 0x3fb8aa3b, v6
	v_add_f32_e32 v5, v67, v5
	v_exp_f32_e32 v87, v6
	v_sub_f32_e32 v6, v28, v4
	v_add_f32_e32 v5, v64, v5
	v_mul_f32_e32 v6, 0x3fb8aa3b, v6
	v_add_f32_e32 v5, v65, v5
	v_exp_f32_e32 v88, v6
	v_sub_f32_e32 v6, v29, v4
	v_add_f32_e32 v5, v62, v5
	v_mul_f32_e32 v6, 0x3fb8aa3b, v6
	v_add_f32_e32 v5, v63, v5
	v_exp_f32_e32 v89, v6
	v_sub_f32_e32 v6, v26, v4
	v_add_f32_e32 v5, v60, v5
	v_mul_f32_e32 v6, 0x3fb8aa3b, v6
	v_add_f32_e32 v5, v61, v5
	v_exp_f32_e32 v90, v6
	v_sub_f32_e32 v6, v27, v4
	v_add_f32_e32 v5, v58, v5
	v_mul_f32_e32 v6, 0x3fb8aa3b, v6
	v_add_f32_e32 v5, v59, v5
	v_exp_f32_e32 v91, v6
	v_sub_f32_e32 v6, v24, v4
	v_add_f32_e32 v5, v56, v5
	v_mul_f32_e32 v6, 0x3fb8aa3b, v6
	v_add_f32_e32 v5, v57, v5
	v_exp_f32_e32 v92, v6
	v_sub_f32_e32 v6, v25, v4
	v_add_f32_e32 v5, v54, v5
	v_mul_f32_e32 v6, 0x3fb8aa3b, v6
	v_add_f32_e32 v5, v55, v5
	v_exp_f32_e32 v93, v6
	v_sub_f32_e32 v6, v22, v4
	v_add_f32_e32 v5, v52, v5
	v_mul_f32_e32 v6, 0x3fb8aa3b, v6
	v_add_f32_e32 v5, v53, v5
	v_exp_f32_e32 v94, v6
	v_sub_f32_e32 v6, v23, v4
	v_add_f32_e32 v5, v50, v5
	v_mul_f32_e32 v6, 0x3fb8aa3b, v6
	v_add_f32_e32 v5, v51, v5
	v_exp_f32_e32 v95, v6
	v_sub_f32_e32 v6, v8, v4
	v_add_f32_e32 v5, v48, v5
	v_mul_f32_e32 v6, 0x3fb8aa3b, v6
	v_add_f32_e32 v5, v49, v5
	v_exp_f32_e32 v97, v6
	v_sub_f32_e32 v6, v9, v4
	v_add_f32_e32 v5, v80, v5
	v_mul_f32_e32 v6, 0x3fb8aa3b, v6
	v_add_f32_e32 v5, v81, v5
	v_exp_f32_e32 v100, v6
	v_sub_f32_e32 v6, v16, v4
	v_add_f32_e32 v5, v82, v5
	v_mul_f32_e32 v6, 0x3fb8aa3b, v6
	v_add_f32_e32 v5, v83, v5
	v_exp_f32_e32 v96, v6
	v_sub_f32_e32 v6, v17, v4
	v_add_f32_e32 v5, v84, v5
	v_mul_f32_e32 v6, 0x3fb8aa3b, v6
	v_add_f32_e32 v5, v85, v5
	v_exp_f32_e32 v98, v6
	v_sub_f32_e32 v6, v10, v4
	v_add_f32_e32 v5, v86, v5
	v_mul_f32_e32 v6, 0x3fb8aa3b, v6
	v_add_f32_e32 v5, v87, v5
	v_exp_f32_e32 v99, v6
	v_sub_f32_e32 v6, v11, v4
	v_add_f32_e32 v5, v88, v5
	v_mul_f32_e32 v6, 0x3fb8aa3b, v6
	v_add_f32_e32 v5, v89, v5
	v_exp_f32_e32 v101, v6
	v_sub_f32_e32 v6, v18, v4
	v_add_f32_e32 v5, v90, v5
	v_mul_f32_e32 v6, 0x3fb8aa3b, v6
	v_add_f32_e32 v5, v91, v5
	v_exp_f32_e32 v102, v6
	v_sub_f32_e32 v6, v19, v4
	v_add_f32_e32 v5, v92, v5
	v_mul_f32_e32 v6, 0x3fb8aa3b, v6
	v_add_f32_e32 v5, v93, v5
	v_exp_f32_e32 v104, v6
	v_sub_f32_e32 v6, v12, v4
	v_add_f32_e32 v5, v94, v5
	v_mul_f32_e32 v6, 0x3fb8aa3b, v6
	v_add_f32_e32 v5, v95, v5
	v_exp_f32_e32 v105, v6
	v_sub_f32_e32 v6, v13, v4
	v_add_f32_e32 v5, v97, v5
	v_mul_f32_e32 v6, 0x3fb8aa3b, v6
	v_add_f32_e32 v5, v100, v5
	v_exp_f32_e32 v108, v6
	v_sub_f32_e32 v6, v20, v4
	v_add_f32_e32 v5, v96, v5
	v_mul_f32_e32 v6, 0x3fb8aa3b, v6
	v_add_f32_e32 v5, v98, v5
	v_exp_f32_e32 v103, v6
	v_sub_f32_e32 v6, v21, v4
	v_add_f32_e32 v5, v99, v5
	v_mul_f32_e32 v6, 0x3fb8aa3b, v6
	v_add_f32_e32 v5, v101, v5
	v_exp_f32_e32 v106, v6
	v_sub_f32_e32 v6, v14, v4
	v_add_f32_e32 v5, v102, v5
	v_mul_f32_e32 v6, 0x3fb8aa3b, v6
	v_add_f32_e32 v5, v104, v5
	v_exp_f32_e32 v107, v6
	v_sub_f32_e32 v6, v15, v4
	v_add_f32_e32 v5, v105, v5
	v_mul_f32_e32 v6, 0x3fb8aa3b, v6
	v_sub_f32_e32 v2, v2, v4
	v_add_f32_e32 v5, v108, v5
	v_exp_f32_e32 v109, v6
	v_mul_f32_e32 v2, 0x3fb8aa3b, v2
	v_sub_f32_e32 v3, v3, v4
	v_add_f32_e32 v5, v103, v5
	v_exp_f32_e32 v110, v2
	v_mul_f32_e32 v3, 0x3fb8aa3b, v3
	v_sub_f32_e32 v0, v0, v4
	v_add_f32_e32 v5, v106, v5
	v_exp_f32_e32 v111, v3
	v_mul_f32_e32 v0, 0x3fb8aa3b, v0
	v_sub_f32_e32 v1, v1, v4
	v_add_f32_e32 v5, v107, v5
	v_exp_f32_e32 v112, v0
	v_mul_f32_e32 v1, 0x3fb8aa3b, v1
	v_add_f32_e32 v5, v109, v5
	v_exp_f32_e32 v113, v1
	v_add_f32_e32 v2, v110, v5
	v_add_f32_e32 v2, v111, v2
	v_add_f32_e32 v0, v112, v2
	v_add_f32_e32 v0, v113, v0
	ds_bpermute_b32 v1, v78, v0
	s_nop 0
	s_mov_b32 s0, 0x360000
	s_nop 0
	s_waitcnt lgkmcnt(0)
	v_add_f32_e32 v114, v0, v1
	ds_bpermute_b32 v115, v79, v114
	v_cvt_pk_bf16_f32 v120, v76, v77
	v_cvt_pk_bf16_f32 v121, v74, v75
	v_cvt_pk_bf16_f32 v122, v72, v73
	v_cvt_pk_bf16_f32 v123, v70, v71
	s_waitcnt vmcnt(11)
	v_mfma_f32_16x16x32_bf16 v[0:3], v[190:193], v[120:123], 0
	s_waitcnt vmcnt(10)
	v_mfma_f32_16x16x32_bf16 v[4:7], v[194:197], v[120:123], 0
	s_waitcnt vmcnt(9)
	v_mfma_f32_16x16x32_bf16 v[8:11], v[198:201], v[120:123], 0
	s_waitcnt vmcnt(8)
	v_mfma_f32_16x16x32_bf16 v[20:23], v[202:205], v[120:123], 0
	global_load_dwordx4 v[190:193], v[246:247], off offset:192
	global_load_dwordx4 v[194:197], v[248:249], off offset:192
	global_load_dwordx4 v[198:201], v[250:251], off offset:192
	global_load_dwordx4 v[202:205], v[252:253], off offset:192
	v_cvt_pk_bf16_f32 v128, v68, v69
	v_cvt_pk_bf16_f32 v129, v66, v67
	v_cvt_pk_bf16_f32 v130, v64, v65
	v_cvt_pk_bf16_f32 v131, v62, v63
	s_waitcnt vmcnt(11)
	v_mfma_f32_16x16x32_bf16 v[0:3], v[206:209], v[128:131], v[0:3]
	s_waitcnt vmcnt(10)
	v_mfma_f32_16x16x32_bf16 v[4:7], v[210:213], v[128:131], v[4:7]
	s_waitcnt vmcnt(9)
	v_mfma_f32_16x16x32_bf16 v[8:11], v[214:217], v[128:131], v[8:11]
	s_waitcnt vmcnt(8)
	v_mfma_f32_16x16x32_bf16 v[12:15], v[218:221], v[128:131], v[20:23]
	global_load_dwordx4 v[206:209], v[246:247], off offset:256
	global_load_dwordx4 v[210:213], v[248:249], off offset:256
	global_load_dwordx4 v[214:217], v[250:251], off offset:256
	global_load_dwordx4 v[218:221], v[252:253], off offset:256
	s_nop 1
	v_cvt_pk_bf16_f32 v60, v60, v61
	v_cvt_pk_bf16_f32 v61, v58, v59
	v_cvt_pk_bf16_f32 v62, v56, v57
	v_cvt_pk_bf16_f32 v63, v54, v55
	s_waitcnt vmcnt(11)
	v_mfma_f32_16x16x32_bf16 v[0:3], v[222:225], v[60:63], v[0:3]
	s_waitcnt vmcnt(10)
	v_mfma_f32_16x16x32_bf16 v[4:7], v[226:229], v[60:63], v[4:7]
	s_waitcnt vmcnt(9)
	v_mfma_f32_16x16x32_bf16 v[8:11], v[230:233], v[60:63], v[8:11]
	s_waitcnt vmcnt(8)
	v_mfma_f32_16x16x32_bf16 v[12:15], v[234:237], v[60:63], v[12:15]
	global_load_dwordx4 v[222:225], v[246:247], off offset:320
	global_load_dwordx4 v[226:229], v[248:249], off offset:320
	global_load_dwordx4 v[230:233], v[250:251], off offset:320
	global_load_dwordx4 v[234:237], v[252:253], off offset:320
	v_cvt_pk_bf16_f32 v70, v52, v53
	v_cvt_pk_bf16_f32 v71, v50, v51
	v_cvt_pk_bf16_f32 v72, v48, v49
	v_cvt_pk_bf16_f32 v73, v80, v81
	s_waitcnt vmcnt(11)
	v_mfma_f32_16x16x32_bf16 v[0:3], v[190:193], v[70:73], v[0:3]
	s_waitcnt vmcnt(10)
	v_mfma_f32_16x16x32_bf16 v[4:7], v[194:197], v[70:73], v[4:7]
	s_waitcnt vmcnt(9)
	v_mfma_f32_16x16x32_bf16 v[8:11], v[198:201], v[70:73], v[8:11]
	s_waitcnt vmcnt(8)
	v_mfma_f32_16x16x32_bf16 v[12:15], v[202:205], v[70:73], v[12:15]
	global_load_dwordx4 v[190:193], v[246:247], off offset:384
	global_load_dwordx4 v[194:197], v[248:249], off offset:384
	global_load_dwordx4 v[198:201], v[250:251], off offset:384
	global_load_dwordx4 v[202:205], v[252:253], off offset:384
	v_cvt_pk_bf16_f32 v48, v82, v83
	v_cvt_pk_bf16_f32 v49, v84, v85
	v_cvt_pk_bf16_f32 v50, v86, v87
	v_cvt_pk_bf16_f32 v51, v88, v89
	s_waitcnt vmcnt(11)
	v_mfma_f32_16x16x32_bf16 v[0:3], v[206:209], v[48:51], v[0:3]
	s_waitcnt vmcnt(10)
	v_mfma_f32_16x16x32_bf16 v[4:7], v[210:213], v[48:51], v[4:7]
	s_waitcnt vmcnt(9)
	v_mfma_f32_16x16x32_bf16 v[8:11], v[214:217], v[48:51], v[8:11]
	s_waitcnt vmcnt(8)
	v_mfma_f32_16x16x32_bf16 v[12:15], v[218:221], v[48:51], v[12:15]
	global_load_dwordx4 v[206:209], v[246:247], off offset:448
	global_load_dwordx4 v[210:213], v[248:249], off offset:448
	global_load_dwordx4 v[214:217], v[250:251], off offset:448
	global_load_dwordx4 v[218:221], v[252:253], off offset:448
	v_cvt_pk_bf16_f32 v64, v90, v91
	v_cvt_pk_bf16_f32 v65, v92, v93
	v_cvt_pk_bf16_f32 v66, v94, v95
	v_cvt_pk_bf16_f32 v67, v97, v100
	s_waitcnt vmcnt(11)
	v_mfma_f32_16x16x32_bf16 v[0:3], v[222:225], v[64:67], v[0:3]
	s_waitcnt vmcnt(10)
	v_mfma_f32_16x16x32_bf16 v[4:7], v[226:229], v[64:67], v[4:7]
	s_waitcnt vmcnt(9)
	v_mfma_f32_16x16x32_bf16 v[8:11], v[230:233], v[64:67], v[8:11]
	s_waitcnt vmcnt(8)
	v_mfma_f32_16x16x32_bf16 v[12:15], v[234:237], v[64:67], v[12:15]
	v_cvt_pk_bf16_f32 v40, v96, v98
	v_cvt_pk_bf16_f32 v41, v99, v101
	v_cvt_pk_bf16_f32 v42, v102, v104
	v_cvt_pk_bf16_f32 v43, v105, v108
	s_waitcnt vmcnt(7)
	v_mfma_f32_16x16x32_bf16 v[0:3], v[190:193], v[40:43], v[0:3]
	s_waitcnt vmcnt(6)
	v_mfma_f32_16x16x32_bf16 v[4:7], v[194:197], v[40:43], v[4:7]
	s_waitcnt vmcnt(5)
	v_mfma_f32_16x16x32_bf16 v[8:11], v[198:201], v[40:43], v[8:11]
	s_waitcnt vmcnt(4)
	v_mfma_f32_16x16x32_bf16 v[12:15], v[202:205], v[40:43], v[12:15]
	s_waitcnt lgkmcnt(0)
	v_add_f32_e32 v44, v114, v115
	v_cvt_pk_bf16_f32 v40, v103, v106
	v_cvt_pk_bf16_f32 v41, v107, v109
	v_cvt_pk_bf16_f32 v42, v110, v111
	v_cvt_pk_bf16_f32 v43, v112, v113
	s_waitcnt vmcnt(3)
	v_mfma_f32_16x16x32_bf16 v[0:3], v[206:209], v[40:43], v[0:3]
	s_waitcnt vmcnt(2)
	v_mfma_f32_16x16x32_bf16 v[4:7], v[210:213], v[40:43], v[4:7]
	s_waitcnt vmcnt(1)
	v_mfma_f32_16x16x32_bf16 v[8:11], v[214:217], v[40:43], v[8:11]
	s_waitcnt vmcnt(0)
	v_mfma_f32_16x16x32_bf16 v[12:15], v[218:221], v[40:43], v[12:15]
	v_add_f32_e32 v16, 0, v44
	v_div_scale_f32 v17, s[0:1], v16, v16, 1.0
	v_rcp_f32_e32 v18, v17
	v_div_scale_f32 v19, vcc, 1.0, v16, 1.0
	s_add_i32 s2, s2, s3
	v_fma_f32 v20, -v17, v18, 1.0
	v_fmac_f32_e32 v18, v20, v18
	v_mul_f32_e32 v20, v19, v18
	v_fma_f32 v21, -v17, v20, v19
	v_fmac_f32_e32 v20, v21, v18
	v_fma_f32 v17, -v17, v20, v19
	v_div_fmas_f32 v17, v17, v18, v20
	v_lshlrev_b64 v[18:19], 11, v[34:35]
	v_div_fixup_f32 v16, v17, v16, 1.0
	v_lshl_add_u64 v[18:19], s[42:43], 0, v[18:19]
	v_lshl_add_u64 v[18:19], v[18:19], 0, s[6:7]
	v_pk_mul_f32 v[2:3], v[16:17], v[2:3] op_sel_hi:[0,1]
	v_pk_mul_f32 v[0:1], v[16:17], v[0:1] op_sel_hi:[0,1]
	v_lshl_add_u64 v[18:19], v[38:39], 1, v[18:19]
	v_cvt_pk_bf16_f32 v0, v0, v1
	v_cvt_pk_bf16_f32 v1, v2, v3
	v_pk_mul_f32 v[2:3], v[16:17], v[4:5] op_sel_hi:[0,1]
	global_store_dwordx2 v[18:19], v[0:1], off
	v_pk_mul_f32 v[0:1], v[16:17], v[6:7] op_sel_hi:[0,1]
	v_cvt_pk_bf16_f32 v2, v2, v3
	v_cvt_pk_bf16_f32 v3, v0, v1
	global_store_dwordx2 v[18:19], v[2:3], off offset:32
	v_pk_mul_f32 v[2:3], v[16:17], v[8:9] op_sel_hi:[0,1]
	v_pk_mul_f32 v[0:1], v[16:17], v[10:11] op_sel_hi:[0,1]
	v_cvt_pk_bf16_f32 v2, v2, v3
	v_cvt_pk_bf16_f32 v3, v0, v1
	s_add_i32 s4, s4, s5
	s_add_i32 s11, s11, s10
	global_store_dwordx2 v[18:19], v[2:3], off offset:64
	v_pk_mul_f32 v[2:3], v[16:17], v[12:13] op_sel_hi:[0,1]
	s_cmpk_gt_i32 s2, 0xfff
	v_pk_mul_f32 v[0:1], v[16:17], v[14:15] op_sel_hi:[0,1]
	v_cvt_pk_bf16_f32 v2, v2, v3
	v_cvt_pk_bf16_f32 v3, v0, v1
	global_store_dwordx2 v[18:19], v[2:3], off offset:96
	s_cbranch_scc0 .LBB0_524
